# phase-0 x copy (f32->bf16): 16 serialized load/store iterations unrolled x4 with 8 loads in flight and counted waits (generic fallback loop kept for other grid sizes)
# baseline (speedup 1.0000x reference)
.LBB0_1073:
	s_waitcnt vmcnt(0)
	v_mov_b32_e32 v0, v192
	s_mov_b64 s[0:1], 0x200000
	v_ashrrev_i32_e32 v1, 31, v0
	v_lshl_add_u64 v[2:3], s[82:83], 0, v[0:1]
	v_cmp_gt_u64_e32 vcc, s[0:1], v[2:3]
	s_and_saveexec_b64 s[6:7], vcc
	v_readlane_b32 s4, v253, 11
	v_readlane_b32 s10, v253, 13
	v_readlane_b32 s12, v253, 24
	v_readlane_b32 s5, v253, 12
	v_readlane_b32 s11, v253, 14
	v_readlane_b32 s13, v253, 25
	v_readlane_b32 s14, v253, 26
	v_readlane_b32 s15, v253, 27
	v_readlane_b32 s16, v253, 28
	v_readlane_b32 s17, v253, 29
	v_readlane_b32 s18, v253, 30
	v_readlane_b32 s19, v253, 31
	v_readlane_b32 s20, v253, 32
	v_readlane_b32 s21, v253, 33
	v_readlane_b32 s22, v253, 34
	v_readlane_b32 s23, v253, 35
	v_readlane_b32 s24, v253, 36
	v_readlane_b32 s25, v253, 37
	v_readlane_b32 s26, v253, 38
	v_readlane_b32 s27, v253, 39
	s_cbranch_execz .LBB0_1076
	v_readlane_b32 s0, v252, 43
	s_add_u32 s0, s62, s0
	v_readlane_b32 s1, v252, 44
	s_addc_u32 s1, s63, s1
	s_mov_b64 s[8:9], 0
	v_lshl_add_u64 v[4:5], v[0:1], 3, s[0:1]
	v_readlane_b32 s0, v252, 45
	v_readlane_b32 s1, v252, 46
	v_mov_b64_e32 v[8:9], v[2:3]
	s_nop 0
	v_lshl_add_u64 v[6:7], v[0:1], 4, s[0:1]
	s_cmp_eq_u32 s38, 0x20000
	s_cbranch_scc0 .Lxc_generic
	s_mov_b32 s8, 4
.LBB0_1075:
	v_lshl_add_u64 v[10:11], s[12:13], 0, v[6:7]
	v_lshl_add_u64 v[14:15], s[14:15], 0, v[6:7]
	global_load_dwordx4 v[214:217], v[10:11], off
	global_load_dwordx4 v[218:221], v[14:15], off
	v_lshl_add_u64 v[6:7], v[6:7], 0, s[10:11]
	v_lshl_add_u64 v[10:11], s[12:13], 0, v[6:7]
	v_lshl_add_u64 v[14:15], s[14:15], 0, v[6:7]
	global_load_dwordx4 v[222:225], v[10:11], off
	global_load_dwordx4 v[226:229], v[14:15], off
	v_lshl_add_u64 v[6:7], v[6:7], 0, s[10:11]
	v_lshl_add_u64 v[10:11], s[12:13], 0, v[6:7]
	v_lshl_add_u64 v[14:15], s[14:15], 0, v[6:7]
	global_load_dwordx4 v[230:233], v[10:11], off
	global_load_dwordx4 v[234:237], v[14:15], off
	v_lshl_add_u64 v[6:7], v[6:7], 0, s[10:11]
	v_lshl_add_u64 v[10:11], s[12:13], 0, v[6:7]
	v_lshl_add_u64 v[14:15], s[14:15], 0, v[6:7]
	global_load_dwordx4 v[238:241], v[10:11], off
	global_load_dwordx4 v[242:245], v[14:15], off
	v_lshl_add_u64 v[6:7], v[6:7], 0, s[10:11]
	s_waitcnt vmcnt(6)
	v_cvt_pk_bf16_f32 v10, v214, v215
	v_cvt_pk_bf16_f32 v11, v216, v217
	v_cvt_pk_bf16_f32 v12, v218, v219
	v_cvt_pk_bf16_f32 v13, v220, v221
	v_add_co_u32_e32 v18, vcc, 0xff000000, v4
	s_nop 1
	v_addc_co_u32_e32 v19, vcc, -1, v5, vcc
	global_store_dwordx2 v[18:19], v[10:11], off
	global_store_dwordx2 v[4:5], v[12:13], off
	v_lshl_add_u64 v[4:5], v[4:5], 0, s[4:5]
	s_waitcnt vmcnt(6)
	v_cvt_pk_bf16_f32 v10, v222, v223
	v_cvt_pk_bf16_f32 v11, v224, v225
	v_cvt_pk_bf16_f32 v12, v226, v227
	v_cvt_pk_bf16_f32 v13, v228, v229
	v_add_co_u32_e32 v18, vcc, 0xff000000, v4
	s_nop 1
	v_addc_co_u32_e32 v19, vcc, -1, v5, vcc
	global_store_dwordx2 v[18:19], v[10:11], off
	global_store_dwordx2 v[4:5], v[12:13], off
	v_lshl_add_u64 v[4:5], v[4:5], 0, s[4:5]
	s_waitcnt vmcnt(6)
	v_cvt_pk_bf16_f32 v10, v230, v231
	v_cvt_pk_bf16_f32 v11, v232, v233
	v_cvt_pk_bf16_f32 v12, v234, v235
	v_cvt_pk_bf16_f32 v13, v236, v237
	v_add_co_u32_e32 v18, vcc, 0xff000000, v4
	s_nop 1
	v_addc_co_u32_e32 v19, vcc, -1, v5, vcc
	global_store_dwordx2 v[18:19], v[10:11], off
	global_store_dwordx2 v[4:5], v[12:13], off
	v_lshl_add_u64 v[4:5], v[4:5], 0, s[4:5]
	s_waitcnt vmcnt(6)
	v_cvt_pk_bf16_f32 v10, v238, v239
	v_cvt_pk_bf16_f32 v11, v240, v241
	v_cvt_pk_bf16_f32 v12, v242, v243
	v_cvt_pk_bf16_f32 v13, v244, v245
	v_add_co_u32_e32 v18, vcc, 0xff000000, v4
	s_nop 1
	v_addc_co_u32_e32 v19, vcc, -1, v5, vcc
	global_store_dwordx2 v[18:19], v[10:11], off
	global_store_dwordx2 v[4:5], v[12:13], off
	v_lshl_add_u64 v[4:5], v[4:5], 0, s[4:5]
	s_sub_i32 s8, s8, 1
	s_cmp_lg_u32 s8, 0
	s_cbranch_scc1 .LBB0_1075
	s_branch .LBB0_1076
.Lxc_generic:
	s_mov_b64 s[8:9], 0
.Lxc_gloop:
	v_lshl_add_u64 v[10:11], s[12:13], 0, v[6:7]
	v_lshl_add_u64 v[14:15], s[14:15], 0, v[6:7]
	global_load_dwordx4 v[10:13], v[10:11], off
	s_nop 0
	global_load_dwordx4 v[14:17], v[14:15], off
	v_add_co_u32_e32 v18, vcc, 0xff000000, v4
	v_lshl_add_u64 v[8:9], v[8:9], 0, s[38:39]
	s_nop 0
	v_addc_co_u32_e32 v19, vcc, -1, v5, vcc
	s_mov_b64 s[0:1], 0x1fffff
	v_cmp_lt_u64_e32 vcc, s[0:1], v[8:9]
	v_lshl_add_u64 v[6:7], v[6:7], 0, s[10:11]
	s_or_b64 s[8:9], vcc, s[8:9]
	s_waitcnt vmcnt(0)
	v_cvt_pk_bf16_f32 v10, v10, v11
	v_cvt_pk_bf16_f32 v11, v12, v13
	v_cvt_pk_bf16_f32 v12, v14, v15
	v_cvt_pk_bf16_f32 v13, v16, v17
	global_store_dwordx2 v[18:19], v[10:11], off
	global_store_dwordx2 v[4:5], v[12:13], off
	v_lshl_add_u64 v[4:5], v[4:5], 0, s[4:5]
	s_andn2_b64 exec, exec, s[8:9]
	s_cbranch_execnz .Lxc_gloop
